# v46: v43 (late restore barrier in all five GEMM loops + int8 epilogue-prefix overlap) + redundant post-barrier lgkmcnt(0) removed
# speedup vs baseline: 1.0051x; 1.0051x over previous
.Lrb_skip_230:
.LBB0_230:
	s_add_u32 s98, s0, 0xfff00000
	s_addc_u32 s99, s1, -1
	s_add_u32 s28, s0, 0xfff00080
	s_addc_u32 s29, s1, -1
	s_add_i32 s51, 0, 0x10000
	s_cmp_eq_u32 s50, 60
	s_cselect_b32 s31, s34, s29
	s_cselect_b32 s30, s35, s28
	v_add_u32_e32 v0, s51, v179
	s_cselect_b32 s29, s27, s43
	s_cselect_b32 s28, s40, s41
	s_add_i32 s77, 0, 0x14000
	ds_read_b128 v[130:133], v0
	ds_read_b128 v[134:137], v0 offset:1024
	ds_read_b128 v[138:141], v0 offset:2048
	ds_read_b128 v[142:145], v0 offset:3072
	v_add_u32_e32 v0, s77, v179
	ds_read_b128 v[146:149], v0
	ds_read_b128 v[150:153], v0 offset:1024
	ds_read_b128 v[154:157], v0 offset:2048
	ds_read_b128 v[158:161], v0 offset:3072
	s_mov_b32 m0, s54
	ds_read_b128 v[174:177], v192
	ds_read_b128 v[180:183], v192 offset:1024
	ds_read_b128 v[184:187], v192 offset:2048
	ds_read_b128 v[188:191], v192 offset:3072
	ds_read_b128 v[200:203], v192 offset:4096
	ds_read_b128 v[204:207], v192 offset:5120
	ds_read_b128 v[208:211], v192 offset:6144
	ds_read_b128 v[212:215], v192 offset:7168
	global_load_lds_dwordx4 v168, s[98:99]
	s_mov_b32 m0, s55
	s_nop 0
	global_load_lds_dwordx4 v164, s[98:99]
	s_add_i32 m0, s14, 0xc000
	s_nop 0
	global_load_lds_dwordx4 v170, s[0:1]
	s_add_i32 m0, s14, 0xe000
	s_nop 0
	global_load_lds_dwordx4 v172, s[0:1]
	s_waitcnt vmcnt(8)
	s_waitcnt lgkmcnt(0)
	s_barrier
	v_mfma_f32_16x16x32_bf16 v[126:129], v[130:133], v[174:177], v[126:129]
	v_mfma_f32_16x16x32_bf16 v[126:129], v[134:137], v[180:183], v[126:129]
	v_mfma_f32_16x16x32_bf16 v[110:113], v[130:133], v[184:187], v[110:113]
	v_mfma_f32_16x16x32_bf16 v[110:113], v[134:137], v[188:191], v[110:113]
	v_mfma_f32_16x16x32_bf16 v[94:97], v[130:133], v[200:203], v[94:97]
	v_mfma_f32_16x16x32_bf16 v[94:97], v[134:137], v[204:207], v[94:97]
	v_mfma_f32_16x16x32_bf16 v[78:81], v[130:133], v[208:211], v[78:81]
	v_mfma_f32_16x16x32_bf16 v[78:81], v[134:137], v[212:215], v[78:81]
	v_mfma_f32_16x16x32_bf16 v[122:125], v[138:141], v[174:177], v[122:125]
	v_mfma_f32_16x16x32_bf16 v[122:125], v[142:145], v[180:183], v[122:125]
	v_mfma_f32_16x16x32_bf16 v[106:109], v[138:141], v[184:187], v[106:109]
	v_mfma_f32_16x16x32_bf16 v[106:109], v[142:145], v[188:191], v[106:109]
	v_mfma_f32_16x16x32_bf16 v[90:93], v[138:141], v[200:203], v[90:93]
	v_mfma_f32_16x16x32_bf16 v[90:93], v[142:145], v[204:207], v[90:93]
	v_mfma_f32_16x16x32_bf16 v[74:77], v[138:141], v[208:211], v[74:77]
	v_mfma_f32_16x16x32_bf16 v[74:77], v[142:145], v[212:215], v[74:77]
	v_mfma_f32_16x16x32_bf16 v[118:121], v[146:149], v[174:177], v[118:121]
	v_mfma_f32_16x16x32_bf16 v[118:121], v[150:153], v[180:183], v[118:121]
	v_mfma_f32_16x16x32_bf16 v[102:105], v[146:149], v[184:187], v[102:105]
	v_mfma_f32_16x16x32_bf16 v[102:105], v[150:153], v[188:191], v[102:105]
	v_mfma_f32_16x16x32_bf16 v[86:89], v[146:149], v[200:203], v[86:89]
	v_mfma_f32_16x16x32_bf16 v[86:89], v[150:153], v[204:207], v[86:89]
	v_mfma_f32_16x16x32_bf16 v[70:73], v[146:149], v[208:211], v[70:73]
	v_mfma_f32_16x16x32_bf16 v[70:73], v[150:153], v[212:215], v[70:73]
	v_mfma_f32_16x16x32_bf16 v[114:117], v[154:157], v[174:177], v[114:117]
	v_mfma_f32_16x16x32_bf16 v[114:117], v[158:161], v[180:183], v[114:117]
	v_mfma_f32_16x16x32_bf16 v[98:101], v[154:157], v[184:187], v[98:101]
	v_mfma_f32_16x16x32_bf16 v[98:101], v[158:161], v[188:191], v[98:101]
	v_mfma_f32_16x16x32_bf16 v[82:85], v[154:157], v[200:203], v[82:85]
	v_mfma_f32_16x16x32_bf16 v[82:85], v[158:161], v[204:207], v[82:85]
	v_mfma_f32_16x16x32_bf16 v[66:69], v[154:157], v[208:211], v[66:69]
	v_mfma_f32_16x16x32_bf16 v[66:69], v[158:161], v[212:215], v[66:69]
	s_barrier
	s_add_i32 s51, s51, s9
	s_mov_b32 m0, s51
	ds_read_b128 v[174:177], v192 offset:16384
	ds_read_b128 v[180:183], v192 offset:17408
	ds_read_b128 v[184:187], v192 offset:18432
	ds_read_b128 v[188:191], v192 offset:19456
	ds_read_b128 v[200:203], v192 offset:20480
	ds_read_b128 v[204:207], v192 offset:21504
	ds_read_b128 v[208:211], v192 offset:22528
	ds_read_b128 v[212:215], v192 offset:23552
	global_load_lds_dwordx4 v166, s[28:29]
	s_add_i32 m0, s51, 0x2000
	s_add_u32 s80, s28, 0x100000
	s_addc_u32 s81, s29, 0
	s_add_i32 s51, s77, s9
	global_load_lds_dwordx4 v162, s[28:29]
	s_mov_b32 m0, s51
	s_nop 0
	global_load_lds_dwordx4 v166, s[80:81]
	s_add_i32 m0, s51, 0x2000
	s_nop 0
	global_load_lds_dwordx4 v162, s[80:81]
	s_waitcnt vmcnt(6)
	s_waitcnt lgkmcnt(0)
	s_barrier
	v_mfma_f32_16x16x32_bf16 v[62:65], v[130:133], v[174:177], v[62:65]
	v_mfma_f32_16x16x32_bf16 v[62:65], v[134:137], v[180:183], v[62:65]
	v_mfma_f32_16x16x32_bf16 v[46:49], v[130:133], v[184:187], v[46:49]
	v_mfma_f32_16x16x32_bf16 v[46:49], v[134:137], v[188:191], v[46:49]
	v_mfma_f32_16x16x32_bf16 v[30:33], v[130:133], v[200:203], v[30:33]
	v_mfma_f32_16x16x32_bf16 v[30:33], v[134:137], v[204:207], v[30:33]
	v_mfma_f32_16x16x32_bf16 v[14:17], v[130:133], v[208:211], v[14:17]
	v_mfma_f32_16x16x32_bf16 v[14:17], v[134:137], v[212:215], v[14:17]
	v_mfma_f32_16x16x32_bf16 v[58:61], v[138:141], v[174:177], v[58:61]
	v_mfma_f32_16x16x32_bf16 v[58:61], v[142:145], v[180:183], v[58:61]
	v_mfma_f32_16x16x32_bf16 v[42:45], v[138:141], v[184:187], v[42:45]
	v_mfma_f32_16x16x32_bf16 v[42:45], v[142:145], v[188:191], v[42:45]
	v_mfma_f32_16x16x32_bf16 v[26:29], v[138:141], v[200:203], v[26:29]
	v_mfma_f32_16x16x32_bf16 v[26:29], v[142:145], v[204:207], v[26:29]
	v_mfma_f32_16x16x32_bf16 v[10:13], v[138:141], v[208:211], v[10:13]
	v_mfma_f32_16x16x32_bf16 v[10:13], v[142:145], v[212:215], v[10:13]
	v_mfma_f32_16x16x32_bf16 v[54:57], v[146:149], v[174:177], v[54:57]
	v_mfma_f32_16x16x32_bf16 v[54:57], v[150:153], v[180:183], v[54:57]
	v_mfma_f32_16x16x32_bf16 v[38:41], v[146:149], v[184:187], v[38:41]
	v_mfma_f32_16x16x32_bf16 v[38:41], v[150:153], v[188:191], v[38:41]
	v_mfma_f32_16x16x32_bf16 v[22:25], v[146:149], v[200:203], v[22:25]
	v_mfma_f32_16x16x32_bf16 v[22:25], v[150:153], v[204:207], v[22:25]
	v_mfma_f32_16x16x32_bf16 v[6:9], v[146:149], v[208:211], v[6:9]
	v_mfma_f32_16x16x32_bf16 v[6:9], v[150:153], v[212:215], v[6:9]
	v_mfma_f32_16x16x32_bf16 v[50:53], v[154:157], v[174:177], v[50:53]
	v_mfma_f32_16x16x32_bf16 v[50:53], v[158:161], v[180:183], v[50:53]
	v_mfma_f32_16x16x32_bf16 v[34:37], v[154:157], v[184:187], v[34:37]
	v_mfma_f32_16x16x32_bf16 v[34:37], v[158:161], v[188:191], v[34:37]
	v_mfma_f32_16x16x32_bf16 v[18:21], v[154:157], v[200:203], v[18:21]
	v_mfma_f32_16x16x32_bf16 v[18:21], v[158:161], v[204:207], v[18:21]
	v_mfma_f32_16x16x32_bf16 v[2:5], v[154:157], v[208:211], v[2:5]
	v_mfma_f32_16x16x32_bf16 v[2:5], v[158:161], v[212:215], v[2:5]
	s_barrier
	s_add_i32 s51, 0, 0x18000
	v_add_u32_e32 v0, s51, v179
	s_add_i32 s77, 0, 0x1c000
	ds_read_b128 v[130:133], v0
	ds_read_b128 v[134:137], v0 offset:1024
	ds_read_b128 v[138:141], v0 offset:2048
	ds_read_b128 v[142:145], v0 offset:3072
	v_add_u32_e32 v0, s77, v179
	ds_read_b128 v[146:149], v0
	ds_read_b128 v[150:153], v0 offset:1024
	ds_read_b128 v[154:157], v0 offset:2048
	ds_read_b128 v[158:161], v0 offset:3072
	s_mov_b32 m0, s14
	ds_read_b128 v[174:177], v192 offset:32768
	ds_read_b128 v[180:183], v192 offset:33792
	ds_read_b128 v[184:187], v192 offset:34816
	ds_read_b128 v[188:191], v192 offset:35840
	ds_read_b128 v[200:203], v192 offset:36864
	ds_read_b128 v[204:207], v192 offset:37888
	ds_read_b128 v[208:211], v192 offset:38912
	ds_read_b128 v[212:215], v192 offset:39936
	global_load_lds_dwordx4 v168, s[30:31]
	s_mov_b32 m0, s15
	s_nop 0
	global_load_lds_dwordx4 v164, s[30:31]
	s_add_u32 s30, s30, 0x100000
	s_addc_u32 s31, s31, 0
	s_mov_b32 m0, s52
	s_nop 0
	global_load_lds_dwordx4 v168, s[30:31]
	s_mov_b32 m0, s53
	s_nop 0
	global_load_lds_dwordx4 v164, s[30:31]
	s_waitcnt vmcnt(8)
	s_waitcnt lgkmcnt(0)
	s_barrier
	v_mfma_f32_16x16x32_bf16 v[126:129], v[130:133], v[174:177], v[126:129]
	v_mfma_f32_16x16x32_bf16 v[126:129], v[134:137], v[180:183], v[126:129]
	v_mfma_f32_16x16x32_bf16 v[110:113], v[130:133], v[184:187], v[110:113]
	v_mfma_f32_16x16x32_bf16 v[110:113], v[134:137], v[188:191], v[110:113]
	v_mfma_f32_16x16x32_bf16 v[94:97], v[130:133], v[200:203], v[94:97]
	v_mfma_f32_16x16x32_bf16 v[94:97], v[134:137], v[204:207], v[94:97]
	v_mfma_f32_16x16x32_bf16 v[78:81], v[130:133], v[208:211], v[78:81]
	v_mfma_f32_16x16x32_bf16 v[78:81], v[134:137], v[212:215], v[78:81]
	v_mfma_f32_16x16x32_bf16 v[122:125], v[138:141], v[174:177], v[122:125]
	v_mfma_f32_16x16x32_bf16 v[122:125], v[142:145], v[180:183], v[122:125]
	v_mfma_f32_16x16x32_bf16 v[106:109], v[138:141], v[184:187], v[106:109]
	v_mfma_f32_16x16x32_bf16 v[106:109], v[142:145], v[188:191], v[106:109]
	v_mfma_f32_16x16x32_bf16 v[90:93], v[138:141], v[200:203], v[90:93]
	v_mfma_f32_16x16x32_bf16 v[90:93], v[142:145], v[204:207], v[90:93]
	v_mfma_f32_16x16x32_bf16 v[74:77], v[138:141], v[208:211], v[74:77]
	v_mfma_f32_16x16x32_bf16 v[74:77], v[142:145], v[212:215], v[74:77]
	v_mfma_f32_16x16x32_bf16 v[118:121], v[146:149], v[174:177], v[118:121]
	v_mfma_f32_16x16x32_bf16 v[118:121], v[150:153], v[180:183], v[118:121]
	v_mfma_f32_16x16x32_bf16 v[102:105], v[146:149], v[184:187], v[102:105]
	v_mfma_f32_16x16x32_bf16 v[102:105], v[150:153], v[188:191], v[102:105]
	v_mfma_f32_16x16x32_bf16 v[86:89], v[146:149], v[200:203], v[86:89]
	v_mfma_f32_16x16x32_bf16 v[86:89], v[150:153], v[204:207], v[86:89]
	v_mfma_f32_16x16x32_bf16 v[70:73], v[146:149], v[208:211], v[70:73]
	v_mfma_f32_16x16x32_bf16 v[70:73], v[150:153], v[212:215], v[70:73]
	v_mfma_f32_16x16x32_bf16 v[114:117], v[154:157], v[174:177], v[114:117]
	v_mfma_f32_16x16x32_bf16 v[114:117], v[158:161], v[180:183], v[114:117]
	v_mfma_f32_16x16x32_bf16 v[98:101], v[154:157], v[184:187], v[98:101]
	v_mfma_f32_16x16x32_bf16 v[98:101], v[158:161], v[188:191], v[98:101]
	v_mfma_f32_16x16x32_bf16 v[82:85], v[154:157], v[200:203], v[82:85]
	v_mfma_f32_16x16x32_bf16 v[82:85], v[158:161], v[204:207], v[82:85]
	v_mfma_f32_16x16x32_bf16 v[66:69], v[154:157], v[208:211], v[66:69]
	v_mfma_f32_16x16x32_bf16 v[66:69], v[158:161], v[212:215], v[66:69]
	s_barrier
	s_add_u32 s98, s28, 0x80
	s_addc_u32 s99, s29, 0
	s_add_i32 s30, s51, s9
	s_mov_b32 m0, s30
	ds_read_b128 v[174:177], v192 offset:49152
	ds_read_b128 v[180:183], v192 offset:50176
	ds_read_b128 v[184:187], v192 offset:51200
	ds_read_b128 v[188:191], v192 offset:52224
	ds_read_b128 v[200:203], v192 offset:53248
	ds_read_b128 v[204:207], v192 offset:54272
	ds_read_b128 v[208:211], v192 offset:55296
	ds_read_b128 v[212:215], v192 offset:56320
	global_load_lds_dwordx4 v166, s[98:99]
	s_add_i32 m0, s30, 0x2000
	s_add_u32 s28, s28, 0x100080
	s_addc_u32 s29, s29, 0
	s_add_i32 s30, s77, s9
	global_load_lds_dwordx4 v162, s[98:99]
	s_mov_b32 m0, s30
	s_nop 0
	global_load_lds_dwordx4 v166, s[28:29]
	s_add_i32 m0, s30, 0x2000
	s_nop 0
	global_load_lds_dwordx4 v162, s[28:29]
	s_waitcnt vmcnt(6)
	s_waitcnt lgkmcnt(0)
	s_barrier
	v_mfma_f32_16x16x32_bf16 v[62:65], v[130:133], v[174:177], v[62:65]
	v_mfma_f32_16x16x32_bf16 v[62:65], v[134:137], v[180:183], v[62:65]
	v_mfma_f32_16x16x32_bf16 v[46:49], v[130:133], v[184:187], v[46:49]
	v_mfma_f32_16x16x32_bf16 v[46:49], v[134:137], v[188:191], v[46:49]
	v_mfma_f32_16x16x32_bf16 v[30:33], v[130:133], v[200:203], v[30:33]
	v_mfma_f32_16x16x32_bf16 v[30:33], v[134:137], v[204:207], v[30:33]
	v_mfma_f32_16x16x32_bf16 v[14:17], v[130:133], v[208:211], v[14:17]
	v_mfma_f32_16x16x32_bf16 v[14:17], v[134:137], v[212:215], v[14:17]
	v_mfma_f32_16x16x32_bf16 v[58:61], v[138:141], v[174:177], v[58:61]
	v_mfma_f32_16x16x32_bf16 v[58:61], v[142:145], v[180:183], v[58:61]
	v_mfma_f32_16x16x32_bf16 v[42:45], v[138:141], v[184:187], v[42:45]
	v_mfma_f32_16x16x32_bf16 v[42:45], v[142:145], v[188:191], v[42:45]
	v_mfma_f32_16x16x32_bf16 v[26:29], v[138:141], v[200:203], v[26:29]
	v_mfma_f32_16x16x32_bf16 v[26:29], v[142:145], v[204:207], v[26:29]
	v_mfma_f32_16x16x32_bf16 v[10:13], v[138:141], v[208:211], v[10:13]
	v_mfma_f32_16x16x32_bf16 v[10:13], v[142:145], v[212:215], v[10:13]
	v_mfma_f32_16x16x32_bf16 v[54:57], v[146:149], v[174:177], v[54:57]
	v_mfma_f32_16x16x32_bf16 v[54:57], v[150:153], v[180:183], v[54:57]
	v_mfma_f32_16x16x32_bf16 v[38:41], v[146:149], v[184:187], v[38:41]
	v_mfma_f32_16x16x32_bf16 v[38:41], v[150:153], v[188:191], v[38:41]
	v_mfma_f32_16x16x32_bf16 v[22:25], v[146:149], v[200:203], v[22:25]
	v_mfma_f32_16x16x32_bf16 v[22:25], v[150:153], v[204:207], v[22:25]
	v_mfma_f32_16x16x32_bf16 v[6:9], v[146:149], v[208:211], v[6:9]
	v_mfma_f32_16x16x32_bf16 v[6:9], v[150:153], v[212:215], v[6:9]
	v_mfma_f32_16x16x32_bf16 v[50:53], v[154:157], v[174:177], v[50:53]
	v_mfma_f32_16x16x32_bf16 v[50:53], v[158:161], v[180:183], v[50:53]
	v_mfma_f32_16x16x32_bf16 v[34:37], v[154:157], v[184:187], v[34:37]
	v_mfma_f32_16x16x32_bf16 v[34:37], v[158:161], v[188:191], v[34:37]
	v_mfma_f32_16x16x32_bf16 v[18:21], v[154:157], v[200:203], v[18:21]
	v_mfma_f32_16x16x32_bf16 v[18:21], v[158:161], v[204:207], v[18:21]
	v_mfma_f32_16x16x32_bf16 v[2:5], v[154:157], v[208:211], v[2:5]
	v_mfma_f32_16x16x32_bf16 v[2:5], v[158:161], v[212:215], v[2:5]
	s_barrier
	s_add_i32 s50, s50, 2
	s_add_u32 s0, s0, 0x100
	s_addc_u32 s1, s1, 0
	s_add_u32 s41, s41, 0x100
	s_addc_u32 s43, s43, 0
	s_cmp_gt_u32 s50, 61
	s_cbranch_scc0 .LBB0_230
	s_and_b64 vcc, exec, s[22:23]
	s_cbranch_vccz .LBB0_233
	s_barrier

.Lspf_j2:
	s_waitcnt lgkmcnt(0)
	s_barrier
	v_mfma_i32_16x16x64_i8 v[142:145], v[34:37], v[174:177], v[142:145]
	v_mfma_i32_16x16x64_i8 v[142:145], v[38:41], v[178:181], v[142:145]
	v_mfma_i32_16x16x64_i8 v[134:137], v[34:37], v[182:185], v[134:137]
	v_mfma_i32_16x16x64_i8 v[134:137], v[38:41], v[186:189], v[134:137]
	v_mfma_i32_16x16x64_i8 v[122:125], v[34:37], v[190:193], v[122:125]
	v_mfma_i32_16x16x64_i8 v[122:125], v[38:41], v[200:203], v[122:125]
	v_mfma_i32_16x16x64_i8 v[106:109], v[34:37], v[204:207], v[106:109]
	v_mfma_i32_16x16x64_i8 v[106:109], v[38:41], v[208:211], v[106:109]
	v_mfma_i32_16x16x64_i8 v[138:141], v[58:61], v[174:177], v[138:141]
	v_mfma_i32_16x16x64_i8 v[138:141], v[62:65], v[178:181], v[138:141]
	v_mfma_i32_16x16x64_i8 v[130:133], v[58:61], v[182:185], v[130:133]
	v_mfma_i32_16x16x64_i8 v[130:133], v[62:65], v[186:189], v[130:133]
	v_mfma_i32_16x16x64_i8 v[114:117], v[58:61], v[190:193], v[114:117]
	v_mfma_i32_16x16x64_i8 v[114:117], v[62:65], v[200:203], v[114:117]
	v_mfma_i32_16x16x64_i8 v[98:101], v[58:61], v[204:207], v[98:101]
	v_mfma_i32_16x16x64_i8 v[98:101], v[62:65], v[208:211], v[98:101]
	v_mfma_i32_16x16x64_i8 v[126:129], v[146:149], v[174:177], v[126:129]
	v_mfma_i32_16x16x64_i8 v[126:129], v[150:153], v[178:181], v[126:129]
	v_mfma_i32_16x16x64_i8 v[110:113], v[146:149], v[182:185], v[110:113]
	v_mfma_i32_16x16x64_i8 v[110:113], v[150:153], v[186:189], v[110:113]
	v_mfma_i32_16x16x64_i8 v[94:97], v[146:149], v[190:193], v[94:97]
	v_mfma_i32_16x16x64_i8 v[94:97], v[150:153], v[200:203], v[94:97]
	v_mfma_i32_16x16x64_i8 v[86:89], v[146:149], v[204:207], v[86:89]
	v_mfma_i32_16x16x64_i8 v[86:89], v[150:153], v[208:211], v[86:89]
	v_mfma_i32_16x16x64_i8 v[118:121], v[154:157], v[174:177], v[118:121]
	v_mfma_i32_16x16x64_i8 v[118:121], v[158:161], v[178:181], v[118:121]
	v_mfma_i32_16x16x64_i8 v[102:105], v[154:157], v[182:185], v[102:105]
	v_mfma_i32_16x16x64_i8 v[102:105], v[158:161], v[186:189], v[102:105]
	v_mfma_i32_16x16x64_i8 v[90:93], v[154:157], v[190:193], v[90:93]
	v_mfma_i32_16x16x64_i8 v[90:93], v[158:161], v[200:203], v[90:93]
	v_mfma_i32_16x16x64_i8 v[82:85], v[154:157], v[204:207], v[82:85]
	v_mfma_i32_16x16x64_i8 v[82:85], v[158:161], v[208:211], v[82:85]
	s_barrier
	s_add_i32 s30, s42, s81
	s_add_u32 s98, s28, 0x80
	s_addc_u32 s99, s29, 0
	s_mov_b32 m0, s30
	ds_read_b128 v[174:177], v250 offset:49152
	ds_read_b128 v[178:181], v250 offset:50176
	ds_read_b128 v[182:185], v250 offset:51200
	ds_read_b128 v[186:189], v250 offset:52224
	ds_read_b128 v[190:193], v250 offset:53248
	ds_read_b128 v[200:203], v250 offset:54272
	ds_read_b128 v[204:207], v250 offset:55296
	ds_read_b128 v[208:211], v250 offset:56320
	global_load_lds_dwordx4 v164, s[98:99]
	s_add_i32 m0, s30, 0x2000
	s_add_u32 s28, s28, 0x80080
	s_addc_u32 s29, s29, 0
	s_add_i32 s30, s43, s81
	global_load_lds_dwordx4 v168, s[98:99]
	s_mov_b32 m0, s30
	s_nop 0
	global_load_lds_dwordx4 v164, s[28:29]
	s_add_i32 m0, s30, 0x2000
	s_nop 0
	global_load_lds_dwordx4 v168, s[28:29]
	s_waitcnt vmcnt(6)
	s_waitcnt lgkmcnt(0)
	s_barrier
	v_mfma_i32_16x16x64_i8 v[78:81], v[34:37], v[174:177], v[78:81]
	v_mfma_i32_16x16x64_i8 v[78:81], v[38:41], v[178:181], v[78:81]
	v_mfma_i32_16x16x64_i8 v[70:73], v[34:37], v[182:185], v[70:73]
	v_mfma_i32_16x16x64_i8 v[70:73], v[38:41], v[186:189], v[70:73]
	v_mfma_i32_16x16x64_i8 v[54:57], v[34:37], v[190:193], v[54:57]
	v_mfma_i32_16x16x64_i8 v[54:57], v[38:41], v[200:203], v[54:57]
	v_mfma_i32_16x16x64_i8 v[2:5], v[34:37], v[204:207], v[2:5]
	v_mfma_i32_16x16x64_i8 v[38:41], v[38:41], v[208:211], v[2:5]
	v_mfma_i32_16x16x64_i8 v[74:77], v[58:61], v[174:177], v[74:77]
	v_mfma_i32_16x16x64_i8 v[74:77], v[62:65], v[178:181], v[74:77]
	v_mfma_i32_16x16x64_i8 v[66:69], v[58:61], v[182:185], v[66:69]
	v_mfma_i32_16x16x64_i8 v[66:69], v[62:65], v[186:189], v[66:69]
	v_mfma_i32_16x16x64_i8 v[50:53], v[58:61], v[190:193], v[50:53]
	v_mfma_i32_16x16x64_i8 v[50:53], v[62:65], v[200:203], v[50:53]
	v_mfma_i32_16x16x64_i8 v[2:5], v[58:61], v[204:207], v[6:9]
	v_mfma_i32_16x16x64_i8 v[34:37], v[62:65], v[208:211], v[2:5]
	v_mfma_i32_16x16x64_i8 v[2:5], v[146:149], v[174:177], v[10:13]
	v_mfma_i32_16x16x64_i8 v[62:65], v[150:153], v[178:181], v[2:5]
	v_mfma_i32_16x16x64_i8 v[2:5], v[154:157], v[174:177], v[14:17]
	v_mfma_i32_16x16x64_i8 v[58:61], v[158:161], v[178:181], v[2:5]
	v_mfma_i32_16x16x64_i8 v[2:5], v[146:149], v[182:185], v[46:49]
	v_mfma_i32_16x16x64_i8 v[46:49], v[150:153], v[186:189], v[2:5]
	v_mfma_i32_16x16x64_i8 v[2:5], v[154:157], v[182:185], v[42:45]
	v_mfma_i32_16x16x64_i8 v[42:45], v[158:161], v[186:189], v[2:5]
	v_mfma_i32_16x16x64_i8 v[2:5], v[146:149], v[190:193], v[30:33]
	v_mfma_i32_16x16x64_i8 v[30:33], v[150:153], v[200:203], v[2:5]
	v_mfma_i32_16x16x64_i8 v[2:5], v[154:157], v[190:193], v[26:29]
	v_mfma_i32_16x16x64_i8 v[26:29], v[158:161], v[200:203], v[2:5]
	v_mfma_i32_16x16x64_i8 v[2:5], v[146:149], v[204:207], v[22:25]
	v_mfma_i32_16x16x64_i8 v[22:25], v[150:153], v[208:211], v[2:5]
	v_mfma_i32_16x16x64_i8 v[2:5], v[154:157], v[204:207], v[18:21]
	v_mfma_i32_16x16x64_i8 v[18:21], v[158:161], v[208:211], v[2:5]
	s_barrier
	s_add_i32 s41, s41, 2
	s_add_u32 s0, s0, 0x100
	s_addc_u32 s1, s1, 0
	s_add_u32 s35, s35, 0x100
	s_addc_u32 s40, s40, 0
	s_cmp_gt_u32 s41, 29
	s_cbranch_scc0 .LBB0_300
.LBB0_303:
	v_readlane_b32 s18, v255, 8
	v_readlane_b32 s19, v255, 9
	s_mov_b64 s[0:1], -1
	s_andn2_b64 vcc, exec, s[18:19]
	v_cndmask_b32_e64 v0, 0, 1, s[18:19]
	v_cmp_ne_u32_e64 s[40:41], 1, v0
	v_mbcnt_lo_u32_b32 v2, -1, 0
	v_mbcnt_hi_u32_b32 v2, -1, v2
	s_cbranch_vccz .LBB0_358
	s_andn2_b64 vcc, exec, s[0:1]
	s_cbranch_vccz .LBB0_367

.Lrb_skip_577:
.LBB0_577:
	s_add_u32 s98, s30, 0xfff80000
	s_addc_u32 s99, s31, -1
	s_add_u32 s34, s30, 0xfff80080
	s_addc_u32 s35, s31, -1
	s_add_i32 s66, 0, 0x10000
	s_cmp_eq_u32 s57, 28
	s_cselect_b32 s43, s19, s35
	s_cselect_b32 s42, s23, s34
	v_add_u32_e32 v0, s66, v228
	s_cselect_b32 s35, s25, s56
	s_cselect_b32 s34, s54, s55
	s_add_i32 s73, 0, 0x14000
	ds_read_b128 v[132:135], v0
	ds_read_b128 v[136:139], v0 offset:1024
	ds_read_b128 v[140:143], v0 offset:2048
	ds_read_b128 v[144:147], v0 offset:3072
	v_add_u32_e32 v0, s73, v228
	ds_read_b128 v[148:151], v0
	ds_read_b128 v[152:155], v0 offset:1024
	ds_read_b128 v[156:159], v0 offset:2048
	ds_read_b128 v[160:163], v0 offset:3072
	s_mov_b32 m0, s50
	ds_read_b128 v[164:167], v230
	ds_read_b128 v[168:171], v230 offset:1024
	ds_read_b128 v[172:175], v230 offset:2048
	ds_read_b128 v[176:179], v230 offset:3072
	ds_read_b128 v[180:183], v230 offset:4096
	ds_read_b128 v[184:187], v230 offset:5120
	ds_read_b128 v[188:191], v230 offset:6144
	ds_read_b128 v[192:195], v230 offset:7168
	global_load_lds_dwordx4 v206, s[98:99]
	s_mov_b32 m0, s51
	s_nop 0
	global_load_lds_dwordx4 v202, s[98:99]
	s_add_i32 m0, s46, 0xc000
	s_nop 0
	global_load_lds_dwordx4 v208, s[30:31]
	s_add_i32 m0, s46, 0xe000
	s_nop 0
	global_load_lds_dwordx4 v210, s[30:31]
	s_waitcnt vmcnt(8)
	s_waitcnt lgkmcnt(0)
	s_barrier
	v_mfma_f32_16x16x32_bf16 v[128:131], v[132:135], v[164:167], v[128:131]
	v_mfma_f32_16x16x32_bf16 v[128:131], v[136:139], v[168:171], v[128:131]
	v_mfma_f32_16x16x32_bf16 v[120:123], v[132:135], v[172:175], v[120:123]
	v_mfma_f32_16x16x32_bf16 v[120:123], v[136:139], v[176:179], v[120:123]
	v_mfma_f32_16x16x32_bf16 v[112:115], v[132:135], v[180:183], v[112:115]
	v_mfma_f32_16x16x32_bf16 v[112:115], v[136:139], v[184:187], v[112:115]
	v_mfma_f32_16x16x32_bf16 v[104:107], v[132:135], v[188:191], v[104:107]
	v_mfma_f32_16x16x32_bf16 v[104:107], v[136:139], v[192:195], v[104:107]
	v_mfma_f32_16x16x32_bf16 v[124:127], v[140:143], v[164:167], v[124:127]
	v_mfma_f32_16x16x32_bf16 v[124:127], v[144:147], v[168:171], v[124:127]
	v_mfma_f32_16x16x32_bf16 v[116:119], v[140:143], v[172:175], v[116:119]
	v_mfma_f32_16x16x32_bf16 v[116:119], v[144:147], v[176:179], v[116:119]
	v_mfma_f32_16x16x32_bf16 v[108:111], v[140:143], v[180:183], v[108:111]
	v_mfma_f32_16x16x32_bf16 v[108:111], v[144:147], v[184:187], v[108:111]
	v_mfma_f32_16x16x32_bf16 v[100:103], v[140:143], v[188:191], v[100:103]
	v_mfma_f32_16x16x32_bf16 v[100:103], v[144:147], v[192:195], v[100:103]
	v_mfma_f32_16x16x32_bf16 v[96:99], v[148:151], v[164:167], v[96:99]
	v_mfma_f32_16x16x32_bf16 v[96:99], v[152:155], v[168:171], v[96:99]
	v_mfma_f32_16x16x32_bf16 v[88:91], v[148:151], v[172:175], v[88:91]
	v_mfma_f32_16x16x32_bf16 v[88:91], v[152:155], v[176:179], v[88:91]
	v_mfma_f32_16x16x32_bf16 v[80:83], v[148:151], v[180:183], v[80:83]
	v_mfma_f32_16x16x32_bf16 v[80:83], v[152:155], v[184:187], v[80:83]
	v_mfma_f32_16x16x32_bf16 v[72:75], v[148:151], v[188:191], v[72:75]
	v_mfma_f32_16x16x32_bf16 v[72:75], v[152:155], v[192:195], v[72:75]
	v_mfma_f32_16x16x32_bf16 v[92:95], v[156:159], v[164:167], v[92:95]
	v_mfma_f32_16x16x32_bf16 v[92:95], v[160:163], v[168:171], v[92:95]
	v_mfma_f32_16x16x32_bf16 v[84:87], v[156:159], v[172:175], v[84:87]
	v_mfma_f32_16x16x32_bf16 v[84:87], v[160:163], v[176:179], v[84:87]
	v_mfma_f32_16x16x32_bf16 v[76:79], v[156:159], v[180:183], v[76:79]
	v_mfma_f32_16x16x32_bf16 v[76:79], v[160:163], v[184:187], v[76:79]
	v_mfma_f32_16x16x32_bf16 v[68:71], v[156:159], v[188:191], v[68:71]
	v_mfma_f32_16x16x32_bf16 v[68:71], v[160:163], v[192:195], v[68:71]
	s_barrier
	s_add_i32 s66, s66, s15
	s_mov_b32 m0, s66
	ds_read_b128 v[164:167], v230 offset:16384
	ds_read_b128 v[168:171], v230 offset:17408
	ds_read_b128 v[172:175], v230 offset:18432
	ds_read_b128 v[176:179], v230 offset:19456
	ds_read_b128 v[180:183], v230 offset:20480
	ds_read_b128 v[184:187], v230 offset:21504
	ds_read_b128 v[188:191], v230 offset:22528
	ds_read_b128 v[192:195], v230 offset:23552
	global_load_lds_dwordx4 v204, s[34:35]
	s_add_i32 m0, s66, 0x2000
	s_add_u32 s66, s34, 0x80000
	s_addc_u32 s67, s35, 0
	s_add_i32 s73, s73, s15
	global_load_lds_dwordx4 v200, s[34:35]
	s_mov_b32 m0, s73
	s_nop 0
	global_load_lds_dwordx4 v204, s[66:67]
	s_add_i32 m0, s73, 0x2000
	s_nop 0
	global_load_lds_dwordx4 v200, s[66:67]
	s_waitcnt vmcnt(6)
	s_waitcnt lgkmcnt(0)
	s_barrier
	v_mfma_f32_16x16x32_bf16 v[64:67], v[132:135], v[164:167], v[64:67]
	v_mfma_f32_16x16x32_bf16 v[64:67], v[136:139], v[168:171], v[64:67]
	v_mfma_f32_16x16x32_bf16 v[56:59], v[132:135], v[172:175], v[56:59]
	v_mfma_f32_16x16x32_bf16 v[56:59], v[136:139], v[176:179], v[56:59]
	v_mfma_f32_16x16x32_bf16 v[48:51], v[132:135], v[180:183], v[48:51]
	v_mfma_f32_16x16x32_bf16 v[48:51], v[136:139], v[184:187], v[48:51]
	v_mfma_f32_16x16x32_bf16 v[40:43], v[132:135], v[188:191], v[40:43]
	v_mfma_f32_16x16x32_bf16 v[40:43], v[136:139], v[192:195], v[40:43]
	v_mfma_f32_16x16x32_bf16 v[60:63], v[140:143], v[164:167], v[60:63]
	v_mfma_f32_16x16x32_bf16 v[60:63], v[144:147], v[168:171], v[60:63]
	v_mfma_f32_16x16x32_bf16 v[52:55], v[140:143], v[172:175], v[52:55]
	v_mfma_f32_16x16x32_bf16 v[52:55], v[144:147], v[176:179], v[52:55]
	v_mfma_f32_16x16x32_bf16 v[44:47], v[140:143], v[180:183], v[44:47]
	v_mfma_f32_16x16x32_bf16 v[44:47], v[144:147], v[184:187], v[44:47]
	v_mfma_f32_16x16x32_bf16 v[36:39], v[140:143], v[188:191], v[36:39]
	v_mfma_f32_16x16x32_bf16 v[36:39], v[144:147], v[192:195], v[36:39]
	v_mfma_f32_16x16x32_bf16 v[32:35], v[148:151], v[164:167], v[32:35]
	v_mfma_f32_16x16x32_bf16 v[32:35], v[152:155], v[168:171], v[32:35]
	v_mfma_f32_16x16x32_bf16 v[28:31], v[156:159], v[164:167], v[28:31]
	v_mfma_f32_16x16x32_bf16 v[28:31], v[160:163], v[168:171], v[28:31]
	v_mfma_f32_16x16x32_bf16 v[24:27], v[148:151], v[172:175], v[24:27]
	v_mfma_f32_16x16x32_bf16 v[24:27], v[152:155], v[176:179], v[24:27]
	v_mfma_f32_16x16x32_bf16 v[20:23], v[156:159], v[172:175], v[20:23]
	v_mfma_f32_16x16x32_bf16 v[20:23], v[160:163], v[176:179], v[20:23]
	v_mfma_f32_16x16x32_bf16 v[16:19], v[148:151], v[180:183], v[16:19]
	v_mfma_f32_16x16x32_bf16 v[16:19], v[152:155], v[184:187], v[16:19]
	v_mfma_f32_16x16x32_bf16 v[12:15], v[156:159], v[180:183], v[12:15]
	v_mfma_f32_16x16x32_bf16 v[12:15], v[160:163], v[184:187], v[12:15]
	v_mfma_f32_16x16x32_bf16 v[8:11], v[148:151], v[188:191], v[8:11]
	v_mfma_f32_16x16x32_bf16 v[8:11], v[152:155], v[192:195], v[8:11]
	v_mfma_f32_16x16x32_bf16 v[2:5], v[156:159], v[188:191], v[4:7]
	v_mfma_f32_16x16x32_bf16 v[2:5], v[160:163], v[192:195], v[2:5]
	s_barrier
	s_add_i32 s66, 0, 0x18000
	v_add_u32_e32 v0, s66, v228
	s_add_i32 s67, 0, 0x1c000
	ds_read_b128 v[132:135], v0
	ds_read_b128 v[136:139], v0 offset:1024
	ds_read_b128 v[140:143], v0 offset:2048
	ds_read_b128 v[144:147], v0 offset:3072
	v_add_u32_e32 v0, s67, v228
	ds_read_b128 v[148:151], v0
	ds_read_b128 v[152:155], v0 offset:1024
	ds_read_b128 v[156:159], v0 offset:2048
	ds_read_b128 v[160:163], v0 offset:3072
	s_mov_b32 m0, s46
	ds_read_b128 v[164:167], v230 offset:32768
	ds_read_b128 v[168:171], v230 offset:33792
	ds_read_b128 v[172:175], v230 offset:34816
	ds_read_b128 v[176:179], v230 offset:35840
	ds_read_b128 v[180:183], v230 offset:36864
	ds_read_b128 v[184:187], v230 offset:37888
	ds_read_b128 v[188:191], v230 offset:38912
	ds_read_b128 v[192:195], v230 offset:39936
	global_load_lds_dwordx4 v206, s[42:43]
	s_mov_b32 m0, s47
	s_nop 0
	global_load_lds_dwordx4 v202, s[42:43]
	s_add_u32 s42, s42, 0x80000
	s_addc_u32 s43, s43, 0
	s_mov_b32 m0, s48
	s_nop 0
	global_load_lds_dwordx4 v206, s[42:43]
	s_mov_b32 m0, s49
	s_nop 0
	global_load_lds_dwordx4 v202, s[42:43]
	s_waitcnt vmcnt(8)
	s_waitcnt lgkmcnt(0)
	s_barrier
	v_mfma_f32_16x16x32_bf16 v[128:131], v[132:135], v[164:167], v[128:131]
	v_mfma_f32_16x16x32_bf16 v[128:131], v[136:139], v[168:171], v[128:131]
	v_mfma_f32_16x16x32_bf16 v[120:123], v[132:135], v[172:175], v[120:123]
	v_mfma_f32_16x16x32_bf16 v[120:123], v[136:139], v[176:179], v[120:123]
	v_mfma_f32_16x16x32_bf16 v[112:115], v[132:135], v[180:183], v[112:115]
	v_mfma_f32_16x16x32_bf16 v[112:115], v[136:139], v[184:187], v[112:115]
	v_mfma_f32_16x16x32_bf16 v[104:107], v[132:135], v[188:191], v[104:107]
	v_mfma_f32_16x16x32_bf16 v[104:107], v[136:139], v[192:195], v[104:107]
	v_mfma_f32_16x16x32_bf16 v[124:127], v[140:143], v[164:167], v[124:127]
	v_mfma_f32_16x16x32_bf16 v[124:127], v[144:147], v[168:171], v[124:127]
	v_mfma_f32_16x16x32_bf16 v[116:119], v[140:143], v[172:175], v[116:119]
	v_mfma_f32_16x16x32_bf16 v[116:119], v[144:147], v[176:179], v[116:119]
	v_mfma_f32_16x16x32_bf16 v[108:111], v[140:143], v[180:183], v[108:111]
	v_mfma_f32_16x16x32_bf16 v[108:111], v[144:147], v[184:187], v[108:111]
	v_mfma_f32_16x16x32_bf16 v[100:103], v[140:143], v[188:191], v[100:103]
	v_mfma_f32_16x16x32_bf16 v[100:103], v[144:147], v[192:195], v[100:103]
	v_mfma_f32_16x16x32_bf16 v[96:99], v[148:151], v[164:167], v[96:99]
	v_mfma_f32_16x16x32_bf16 v[96:99], v[152:155], v[168:171], v[96:99]
	v_mfma_f32_16x16x32_bf16 v[88:91], v[148:151], v[172:175], v[88:91]
	v_mfma_f32_16x16x32_bf16 v[88:91], v[152:155], v[176:179], v[88:91]
	v_mfma_f32_16x16x32_bf16 v[80:83], v[148:151], v[180:183], v[80:83]
	v_mfma_f32_16x16x32_bf16 v[80:83], v[152:155], v[184:187], v[80:83]
	v_mfma_f32_16x16x32_bf16 v[72:75], v[148:151], v[188:191], v[72:75]
	v_mfma_f32_16x16x32_bf16 v[72:75], v[152:155], v[192:195], v[72:75]
	v_mfma_f32_16x16x32_bf16 v[92:95], v[156:159], v[164:167], v[92:95]
	v_mfma_f32_16x16x32_bf16 v[92:95], v[160:163], v[168:171], v[92:95]
	v_mfma_f32_16x16x32_bf16 v[84:87], v[156:159], v[172:175], v[84:87]
	v_mfma_f32_16x16x32_bf16 v[84:87], v[160:163], v[176:179], v[84:87]
	v_mfma_f32_16x16x32_bf16 v[76:79], v[156:159], v[180:183], v[76:79]
	v_mfma_f32_16x16x32_bf16 v[76:79], v[160:163], v[184:187], v[76:79]
	v_mfma_f32_16x16x32_bf16 v[68:71], v[156:159], v[188:191], v[68:71]
	v_mfma_f32_16x16x32_bf16 v[68:71], v[160:163], v[192:195], v[68:71]
	s_barrier
	s_add_i32 s42, s66, s15
	s_add_u32 s98, s34, 0x80
	s_addc_u32 s99, s35, 0
	s_mov_b32 m0, s42
	ds_read_b128 v[164:167], v230 offset:49152
	ds_read_b128 v[168:171], v230 offset:50176
	ds_read_b128 v[172:175], v230 offset:51200
	ds_read_b128 v[176:179], v230 offset:52224
	ds_read_b128 v[180:183], v230 offset:53248
	ds_read_b128 v[184:187], v230 offset:54272
	ds_read_b128 v[188:191], v230 offset:55296
	ds_read_b128 v[192:195], v230 offset:56320
	global_load_lds_dwordx4 v204, s[98:99]
	s_add_i32 m0, s42, 0x2000
	s_add_u32 s34, s34, 0x80080
	s_addc_u32 s35, s35, 0
	s_add_i32 s42, s67, s15
	global_load_lds_dwordx4 v200, s[98:99]
	s_mov_b32 m0, s42
	s_nop 0
	global_load_lds_dwordx4 v204, s[34:35]
	s_add_i32 m0, s42, 0x2000
	s_nop 0
	global_load_lds_dwordx4 v200, s[34:35]
	s_waitcnt vmcnt(6)
	s_waitcnt lgkmcnt(0)
	s_barrier
	v_mfma_f32_16x16x32_bf16 v[64:67], v[132:135], v[164:167], v[64:67]
	v_mfma_f32_16x16x32_bf16 v[64:67], v[136:139], v[168:171], v[64:67]
	v_mfma_f32_16x16x32_bf16 v[56:59], v[132:135], v[172:175], v[56:59]
	v_mfma_f32_16x16x32_bf16 v[56:59], v[136:139], v[176:179], v[56:59]
	v_mfma_f32_16x16x32_bf16 v[48:51], v[132:135], v[180:183], v[48:51]
	v_mfma_f32_16x16x32_bf16 v[48:51], v[136:139], v[184:187], v[48:51]
	v_mfma_f32_16x16x32_bf16 v[40:43], v[132:135], v[188:191], v[40:43]
	v_mfma_f32_16x16x32_bf16 v[40:43], v[136:139], v[192:195], v[40:43]
	v_mfma_f32_16x16x32_bf16 v[60:63], v[140:143], v[164:167], v[60:63]
	v_mfma_f32_16x16x32_bf16 v[60:63], v[144:147], v[168:171], v[60:63]
	v_mfma_f32_16x16x32_bf16 v[52:55], v[140:143], v[172:175], v[52:55]
	v_mfma_f32_16x16x32_bf16 v[52:55], v[144:147], v[176:179], v[52:55]
	v_mfma_f32_16x16x32_bf16 v[44:47], v[140:143], v[180:183], v[44:47]
	v_mfma_f32_16x16x32_bf16 v[44:47], v[144:147], v[184:187], v[44:47]
	v_mfma_f32_16x16x32_bf16 v[36:39], v[140:143], v[188:191], v[36:39]
	v_mfma_f32_16x16x32_bf16 v[36:39], v[144:147], v[192:195], v[36:39]
	v_mfma_f32_16x16x32_bf16 v[32:35], v[148:151], v[164:167], v[32:35]
	v_mfma_f32_16x16x32_bf16 v[32:35], v[152:155], v[168:171], v[32:35]
	v_mfma_f32_16x16x32_bf16 v[28:31], v[156:159], v[164:167], v[28:31]
	v_mfma_f32_16x16x32_bf16 v[28:31], v[160:163], v[168:171], v[28:31]
	v_mfma_f32_16x16x32_bf16 v[24:27], v[148:151], v[172:175], v[24:27]
	v_mfma_f32_16x16x32_bf16 v[24:27], v[152:155], v[176:179], v[24:27]
	v_mfma_f32_16x16x32_bf16 v[20:23], v[156:159], v[172:175], v[20:23]
	v_mfma_f32_16x16x32_bf16 v[20:23], v[160:163], v[176:179], v[20:23]
	v_mfma_f32_16x16x32_bf16 v[16:19], v[148:151], v[180:183], v[16:19]
	v_mfma_f32_16x16x32_bf16 v[16:19], v[152:155], v[184:187], v[16:19]
	v_mfma_f32_16x16x32_bf16 v[12:15], v[156:159], v[180:183], v[12:15]
	v_mfma_f32_16x16x32_bf16 v[12:15], v[160:163], v[184:187], v[12:15]
	v_mfma_f32_16x16x32_bf16 v[6:9], v[148:151], v[188:191], v[8:11]
	v_mfma_f32_16x16x32_bf16 v[8:11], v[152:155], v[192:195], v[6:9]
	v_mfma_f32_16x16x32_bf16 v[2:5], v[156:159], v[188:191], v[2:5]
	v_mfma_f32_16x16x32_bf16 v[4:7], v[160:163], v[192:195], v[2:5]
	s_barrier
	s_add_i32 s57, s57, 2
	s_add_u32 s30, s30, 0x100
	s_addc_u32 s31, s31, 0
	s_add_u32 s55, s55, 0x100
	s_addc_u32 s56, s56, 0
	s_cmp_gt_u32 s57, 29
	s_cbranch_scc0 .LBB0_577
	s_and_b64 vcc, exec, s[20:21]
	s_cbranch_vccz .LBB0_580
	s_barrier

.Lrb_skip_779:
.LBB0_779:
	s_add_u32 s98, s30, 0xfff80000
	s_addc_u32 s99, s31, -1
	s_add_u32 s34, s30, 0xfff80080
	s_addc_u32 s35, s31, -1
	s_add_i32 s66, 0, 0x10000
	s_cmp_eq_u32 s57, 28
	s_cselect_b32 s43, s25, s35
	s_cselect_b32 s42, s53, s34
	s_cselect_b32 s35, s23, s56
	s_cselect_b32 s34, s54, s55
	s_add_i32 s73, 0, 0x14000
	v_add_u32_e32 v114, s66, v157
	v_add_u32_e32 v156, s73, v157
	ds_read_b128 v[90:93], v114
	ds_read_b128 v[94:97], v114 offset:1024
	ds_read_b128 v[106:109], v114 offset:2048
	ds_read_b128 v[114:117], v114 offset:3072
	ds_read_b128 v[162:165], v156
	ds_read_b128 v[166:169], v156 offset:1024
	ds_read_b128 v[170:173], v156 offset:2048
	ds_read_b128 v[174:177], v156 offset:3072
	s_mov_b32 m0, s50
	ds_read_b128 v[178:181], v161
	ds_read_b128 v[182:185], v161 offset:1024
	ds_read_b128 v[186:189], v161 offset:2048
	ds_read_b128 v[190:193], v161 offset:3072
	ds_read_b128 v[200:203], v161 offset:4096
	ds_read_b128 v[204:207], v161 offset:5120
	ds_read_b128 v[208:211], v161 offset:6144
	ds_read_b128 v[212:215], v161 offset:7168
	global_load_lds_dwordx4 v150, s[98:99]
	s_mov_b32 m0, s51
	s_nop 0
	global_load_lds_dwordx4 v148, s[98:99]
	s_add_i32 m0, s14, 0xc000
	s_nop 0
	global_load_lds_dwordx4 v152, s[30:31]
	s_add_i32 m0, s14, 0xe000
	s_nop 0
	global_load_lds_dwordx4 v154, s[30:31]
	s_waitcnt vmcnt(8)
	s_waitcnt lgkmcnt(0)
	s_barrier
	v_mfma_i32_16x16x64_i8 v[142:145], v[90:93], v[178:181], v[142:145]
	v_mfma_i32_16x16x64_i8 v[142:145], v[94:97], v[182:185], v[142:145]
	v_mfma_i32_16x16x64_i8 v[126:129], v[90:93], v[186:189], v[126:129]
	v_mfma_i32_16x16x64_i8 v[126:129], v[94:97], v[190:193], v[126:129]
	v_mfma_i32_16x16x64_i8 v[102:105], v[90:93], v[200:203], v[102:105]
	v_mfma_i32_16x16x64_i8 v[102:105], v[94:97], v[204:207], v[102:105]
	v_mfma_i32_16x16x64_i8 v[78:81], v[90:93], v[208:211], v[78:81]
	v_mfma_i32_16x16x64_i8 v[78:81], v[94:97], v[212:215], v[78:81]
	v_mfma_i32_16x16x64_i8 v[138:141], v[106:109], v[178:181], v[138:141]
	v_mfma_i32_16x16x64_i8 v[138:141], v[114:117], v[182:185], v[138:141]
	v_mfma_i32_16x16x64_i8 v[122:125], v[106:109], v[186:189], v[122:125]
	v_mfma_i32_16x16x64_i8 v[122:125], v[114:117], v[190:193], v[122:125]
	v_mfma_i32_16x16x64_i8 v[98:101], v[106:109], v[200:203], v[98:101]
	v_mfma_i32_16x16x64_i8 v[98:101], v[114:117], v[204:207], v[98:101]
	v_mfma_i32_16x16x64_i8 v[74:77], v[106:109], v[208:211], v[74:77]
	v_mfma_i32_16x16x64_i8 v[74:77], v[114:117], v[212:215], v[74:77]
	v_mfma_i32_16x16x64_i8 v[134:137], v[162:165], v[178:181], v[134:137]
	v_mfma_i32_16x16x64_i8 v[134:137], v[166:169], v[182:185], v[134:137]
	v_mfma_i32_16x16x64_i8 v[118:121], v[162:165], v[186:189], v[118:121]
	v_mfma_i32_16x16x64_i8 v[118:121], v[166:169], v[190:193], v[118:121]
	v_mfma_i32_16x16x64_i8 v[86:89], v[162:165], v[200:203], v[86:89]
	v_mfma_i32_16x16x64_i8 v[86:89], v[166:169], v[204:207], v[86:89]
	v_mfma_i32_16x16x64_i8 v[70:73], v[162:165], v[208:211], v[70:73]
	v_mfma_i32_16x16x64_i8 v[70:73], v[166:169], v[212:215], v[70:73]
	v_mfma_i32_16x16x64_i8 v[130:133], v[170:173], v[178:181], v[130:133]
	v_mfma_i32_16x16x64_i8 v[130:133], v[174:177], v[182:185], v[130:133]
	v_mfma_i32_16x16x64_i8 v[110:113], v[170:173], v[186:189], v[110:113]
	v_mfma_i32_16x16x64_i8 v[110:113], v[174:177], v[190:193], v[110:113]
	v_mfma_i32_16x16x64_i8 v[82:85], v[170:173], v[200:203], v[82:85]
	v_mfma_i32_16x16x64_i8 v[82:85], v[174:177], v[204:207], v[82:85]
	v_mfma_i32_16x16x64_i8 v[66:69], v[170:173], v[208:211], v[66:69]
	v_mfma_i32_16x16x64_i8 v[66:69], v[174:177], v[212:215], v[66:69]
	s_barrier
	s_add_i32 s66, s66, s9
	s_mov_b32 m0, s66
	ds_read_b128 v[178:181], v161 offset:16384
	ds_read_b128 v[182:185], v161 offset:17408
	ds_read_b128 v[186:189], v161 offset:18432
	ds_read_b128 v[190:193], v161 offset:19456
	ds_read_b128 v[200:203], v161 offset:20480
	ds_read_b128 v[204:207], v161 offset:21504
	ds_read_b128 v[208:211], v161 offset:22528
	ds_read_b128 v[212:215], v161 offset:23552
	global_load_lds_dwordx4 v0, s[34:35]
	s_add_i32 m0, s66, 0x2000
	s_add_u32 s66, s34, 0x80000
	s_addc_u32 s67, s35, 0
	s_add_i32 s73, s73, s9
	global_load_lds_dwordx4 v146, s[34:35]
	s_mov_b32 m0, s73
	s_nop 0
	global_load_lds_dwordx4 v0, s[66:67]
	s_add_i32 m0, s73, 0x2000
	s_nop 0
	global_load_lds_dwordx4 v146, s[66:67]
	s_waitcnt vmcnt(6)
	s_waitcnt lgkmcnt(0)
	s_barrier
	v_mfma_i32_16x16x64_i8 v[62:65], v[90:93], v[178:181], v[62:65]
	v_mfma_i32_16x16x64_i8 v[62:65], v[94:97], v[182:185], v[62:65]
	v_mfma_i32_16x16x64_i8 v[46:49], v[90:93], v[186:189], v[46:49]
	v_mfma_i32_16x16x64_i8 v[46:49], v[94:97], v[190:193], v[46:49]
	v_mfma_i32_16x16x64_i8 v[30:33], v[90:93], v[200:203], v[30:33]
	v_mfma_i32_16x16x64_i8 v[30:33], v[94:97], v[204:207], v[30:33]
	v_mfma_i32_16x16x64_i8 v[14:17], v[90:93], v[208:211], v[14:17]
	v_mfma_i32_16x16x64_i8 v[14:17], v[94:97], v[212:215], v[14:17]
	v_mfma_i32_16x16x64_i8 v[58:61], v[106:109], v[178:181], v[58:61]
	v_mfma_i32_16x16x64_i8 v[58:61], v[114:117], v[182:185], v[58:61]
	v_mfma_i32_16x16x64_i8 v[42:45], v[106:109], v[186:189], v[42:45]
	v_mfma_i32_16x16x64_i8 v[42:45], v[114:117], v[190:193], v[42:45]
	v_mfma_i32_16x16x64_i8 v[26:29], v[106:109], v[200:203], v[26:29]
	v_mfma_i32_16x16x64_i8 v[26:29], v[114:117], v[204:207], v[26:29]
	v_mfma_i32_16x16x64_i8 v[10:13], v[106:109], v[208:211], v[10:13]
	v_mfma_i32_16x16x64_i8 v[10:13], v[114:117], v[212:215], v[10:13]
	v_mfma_i32_16x16x64_i8 v[54:57], v[162:165], v[178:181], v[54:57]
	v_mfma_i32_16x16x64_i8 v[54:57], v[166:169], v[182:185], v[54:57]
	v_mfma_i32_16x16x64_i8 v[38:41], v[162:165], v[186:189], v[38:41]
	v_mfma_i32_16x16x64_i8 v[38:41], v[166:169], v[190:193], v[38:41]
	v_mfma_i32_16x16x64_i8 v[22:25], v[162:165], v[200:203], v[22:25]
	v_mfma_i32_16x16x64_i8 v[22:25], v[166:169], v[204:207], v[22:25]
	v_mfma_i32_16x16x64_i8 v[6:9], v[162:165], v[208:211], v[6:9]
	v_mfma_i32_16x16x64_i8 v[6:9], v[166:169], v[212:215], v[6:9]
	v_mfma_i32_16x16x64_i8 v[50:53], v[170:173], v[178:181], v[50:53]
	v_mfma_i32_16x16x64_i8 v[50:53], v[174:177], v[182:185], v[50:53]
	v_mfma_i32_16x16x64_i8 v[34:37], v[170:173], v[186:189], v[34:37]
	v_mfma_i32_16x16x64_i8 v[34:37], v[174:177], v[190:193], v[34:37]
	v_mfma_i32_16x16x64_i8 v[18:21], v[170:173], v[200:203], v[18:21]
	v_mfma_i32_16x16x64_i8 v[18:21], v[174:177], v[204:207], v[18:21]
	v_mfma_i32_16x16x64_i8 v[2:5], v[170:173], v[208:211], v[2:5]
	v_mfma_i32_16x16x64_i8 v[2:5], v[174:177], v[212:215], v[2:5]
	s_barrier
	s_add_i32 s66, 0, 0x18000
	s_add_i32 s67, 0, 0x1c000
	v_add_u32_e32 v114, s66, v157
	v_add_u32_e32 v156, s67, v157
	ds_read_b128 v[90:93], v114
	ds_read_b128 v[94:97], v114 offset:1024
	ds_read_b128 v[106:109], v114 offset:2048
	ds_read_b128 v[114:117], v114 offset:3072
	ds_read_b128 v[162:165], v156
	ds_read_b128 v[166:169], v156 offset:1024
	ds_read_b128 v[170:173], v156 offset:2048
	ds_read_b128 v[174:177], v156 offset:3072
	s_mov_b32 m0, s14
	ds_read_b128 v[178:181], v161 offset:32768
	ds_read_b128 v[182:185], v161 offset:33792
	ds_read_b128 v[186:189], v161 offset:34816
	ds_read_b128 v[190:193], v161 offset:35840
	ds_read_b128 v[200:203], v161 offset:36864
	ds_read_b128 v[204:207], v161 offset:37888
	ds_read_b128 v[208:211], v161 offset:38912
	ds_read_b128 v[212:215], v161 offset:39936
	global_load_lds_dwordx4 v150, s[42:43]
	s_mov_b32 m0, s15
	s_nop 0
	global_load_lds_dwordx4 v148, s[42:43]
	s_add_u32 s42, s42, 0x80000
	s_addc_u32 s43, s43, 0
	s_mov_b32 m0, s46
	s_nop 0
	global_load_lds_dwordx4 v150, s[42:43]
	s_mov_b32 m0, s47
	s_nop 0
	global_load_lds_dwordx4 v148, s[42:43]
	s_waitcnt vmcnt(8)
	s_waitcnt lgkmcnt(0)
	s_barrier
	v_mfma_i32_16x16x64_i8 v[142:145], v[90:93], v[178:181], v[142:145]
	v_mfma_i32_16x16x64_i8 v[142:145], v[94:97], v[182:185], v[142:145]
	v_mfma_i32_16x16x64_i8 v[126:129], v[90:93], v[186:189], v[126:129]
	v_mfma_i32_16x16x64_i8 v[126:129], v[94:97], v[190:193], v[126:129]
	v_mfma_i32_16x16x64_i8 v[102:105], v[90:93], v[200:203], v[102:105]
	v_mfma_i32_16x16x64_i8 v[102:105], v[94:97], v[204:207], v[102:105]
	v_mfma_i32_16x16x64_i8 v[78:81], v[90:93], v[208:211], v[78:81]
	v_mfma_i32_16x16x64_i8 v[78:81], v[94:97], v[212:215], v[78:81]
	v_mfma_i32_16x16x64_i8 v[138:141], v[106:109], v[178:181], v[138:141]
	v_mfma_i32_16x16x64_i8 v[138:141], v[114:117], v[182:185], v[138:141]
	v_mfma_i32_16x16x64_i8 v[122:125], v[106:109], v[186:189], v[122:125]
	v_mfma_i32_16x16x64_i8 v[122:125], v[114:117], v[190:193], v[122:125]
	v_mfma_i32_16x16x64_i8 v[98:101], v[106:109], v[200:203], v[98:101]
	v_mfma_i32_16x16x64_i8 v[98:101], v[114:117], v[204:207], v[98:101]
	v_mfma_i32_16x16x64_i8 v[74:77], v[106:109], v[208:211], v[74:77]
	v_mfma_i32_16x16x64_i8 v[74:77], v[114:117], v[212:215], v[74:77]
	v_mfma_i32_16x16x64_i8 v[134:137], v[162:165], v[178:181], v[134:137]
	v_mfma_i32_16x16x64_i8 v[134:137], v[166:169], v[182:185], v[134:137]
	v_mfma_i32_16x16x64_i8 v[118:121], v[162:165], v[186:189], v[118:121]
	v_mfma_i32_16x16x64_i8 v[118:121], v[166:169], v[190:193], v[118:121]
	v_mfma_i32_16x16x64_i8 v[86:89], v[162:165], v[200:203], v[86:89]
	v_mfma_i32_16x16x64_i8 v[86:89], v[166:169], v[204:207], v[86:89]
	v_mfma_i32_16x16x64_i8 v[70:73], v[162:165], v[208:211], v[70:73]
	v_mfma_i32_16x16x64_i8 v[70:73], v[166:169], v[212:215], v[70:73]
	v_mfma_i32_16x16x64_i8 v[130:133], v[170:173], v[178:181], v[130:133]
	v_mfma_i32_16x16x64_i8 v[130:133], v[174:177], v[182:185], v[130:133]
	v_mfma_i32_16x16x64_i8 v[110:113], v[170:173], v[186:189], v[110:113]
	v_mfma_i32_16x16x64_i8 v[110:113], v[174:177], v[190:193], v[110:113]
	v_mfma_i32_16x16x64_i8 v[82:85], v[170:173], v[200:203], v[82:85]
	v_mfma_i32_16x16x64_i8 v[82:85], v[174:177], v[204:207], v[82:85]
	v_mfma_i32_16x16x64_i8 v[66:69], v[170:173], v[208:211], v[66:69]
	v_mfma_i32_16x16x64_i8 v[66:69], v[174:177], v[212:215], v[66:69]
	s_barrier
	s_add_u32 s98, s34, 0x80
	s_addc_u32 s99, s35, 0
	s_add_i32 s42, s66, s9
	s_mov_b32 m0, s42
	ds_read_b128 v[178:181], v161 offset:49152
	ds_read_b128 v[182:185], v161 offset:50176
	ds_read_b128 v[186:189], v161 offset:51200
	ds_read_b128 v[190:193], v161 offset:52224
	ds_read_b128 v[200:203], v161 offset:53248
	ds_read_b128 v[204:207], v161 offset:54272
	ds_read_b128 v[208:211], v161 offset:55296
	ds_read_b128 v[212:215], v161 offset:56320
	global_load_lds_dwordx4 v0, s[98:99]
	s_add_i32 m0, s42, 0x2000
	s_add_u32 s34, s34, 0x80080
	s_addc_u32 s35, s35, 0
	s_add_i32 s42, s67, s9
	global_load_lds_dwordx4 v146, s[98:99]
	s_mov_b32 m0, s42
	s_nop 0
	global_load_lds_dwordx4 v0, s[34:35]
	s_add_i32 m0, s42, 0x2000
	s_nop 0
	global_load_lds_dwordx4 v146, s[34:35]
	s_waitcnt vmcnt(6)
	s_waitcnt lgkmcnt(0)
	s_barrier
	v_mfma_i32_16x16x64_i8 v[62:65], v[90:93], v[178:181], v[62:65]
	v_mfma_i32_16x16x64_i8 v[62:65], v[94:97], v[182:185], v[62:65]
	v_mfma_i32_16x16x64_i8 v[46:49], v[90:93], v[186:189], v[46:49]
	v_mfma_i32_16x16x64_i8 v[46:49], v[94:97], v[190:193], v[46:49]
	v_mfma_i32_16x16x64_i8 v[30:33], v[90:93], v[200:203], v[30:33]
	v_mfma_i32_16x16x64_i8 v[30:33], v[94:97], v[204:207], v[30:33]
	v_mfma_i32_16x16x64_i8 v[14:17], v[90:93], v[208:211], v[14:17]
	v_mfma_i32_16x16x64_i8 v[14:17], v[94:97], v[212:215], v[14:17]
	v_mfma_i32_16x16x64_i8 v[58:61], v[106:109], v[178:181], v[58:61]
	v_mfma_i32_16x16x64_i8 v[58:61], v[114:117], v[182:185], v[58:61]
	v_mfma_i32_16x16x64_i8 v[42:45], v[106:109], v[186:189], v[42:45]
	v_mfma_i32_16x16x64_i8 v[42:45], v[114:117], v[190:193], v[42:45]
	v_mfma_i32_16x16x64_i8 v[26:29], v[106:109], v[200:203], v[26:29]
	v_mfma_i32_16x16x64_i8 v[26:29], v[114:117], v[204:207], v[26:29]
	v_mfma_i32_16x16x64_i8 v[10:13], v[106:109], v[208:211], v[10:13]
	v_mfma_i32_16x16x64_i8 v[10:13], v[114:117], v[212:215], v[10:13]
	v_mfma_i32_16x16x64_i8 v[54:57], v[162:165], v[178:181], v[54:57]
	v_mfma_i32_16x16x64_i8 v[54:57], v[166:169], v[182:185], v[54:57]
	v_mfma_i32_16x16x64_i8 v[38:41], v[162:165], v[186:189], v[38:41]
	v_mfma_i32_16x16x64_i8 v[38:41], v[166:169], v[190:193], v[38:41]
	v_mfma_i32_16x16x64_i8 v[22:25], v[162:165], v[200:203], v[22:25]
	v_mfma_i32_16x16x64_i8 v[22:25], v[166:169], v[204:207], v[22:25]
	v_mfma_i32_16x16x64_i8 v[6:9], v[162:165], v[208:211], v[6:9]
	v_mfma_i32_16x16x64_i8 v[6:9], v[166:169], v[212:215], v[6:9]
	v_mfma_i32_16x16x64_i8 v[50:53], v[170:173], v[178:181], v[50:53]
	v_mfma_i32_16x16x64_i8 v[50:53], v[174:177], v[182:185], v[50:53]
	v_mfma_i32_16x16x64_i8 v[34:37], v[170:173], v[186:189], v[34:37]
	v_mfma_i32_16x16x64_i8 v[34:37], v[174:177], v[190:193], v[34:37]
	v_mfma_i32_16x16x64_i8 v[18:21], v[170:173], v[200:203], v[18:21]
	v_mfma_i32_16x16x64_i8 v[18:21], v[174:177], v[204:207], v[18:21]
	v_mfma_i32_16x16x64_i8 v[2:5], v[170:173], v[208:211], v[2:5]
	v_mfma_i32_16x16x64_i8 v[2:5], v[174:177], v[212:215], v[2:5]
	s_barrier
	s_add_i32 s57, s57, 2
	s_add_u32 s30, s30, 0x100
	s_addc_u32 s31, s31, 0
	s_add_u32 s55, s55, 0x100
	s_addc_u32 s56, s56, 0
	s_cmp_gt_u32 s57, 29
	s_cbranch_scc0 .LBB0_779
	s_and_b64 vcc, exec, s[20:21]
	s_mov_b32 s54, 0x5c401000
	s_cbranch_vccz .LBB0_782
	s_barrier

.Lrb_skip_801:
.LBB0_801:
	s_add_u32 s98, s30, 0xfff00000
	s_addc_u32 s99, s31, -1
	s_add_u32 s34, s30, 0xfff00080
	s_addc_u32 s35, s31, -1
	s_add_i32 s54, 0, 0x10000
	s_cmp_eq_u32 s53, 60
	s_cselect_b32 s41, s25, s35
	s_cselect_b32 s40, s49, s34
	s_cselect_b32 s35, s23, s52
	s_cselect_b32 s34, s50, s51
	s_add_i32 s56, 0, 0x14000
	v_add_u32_e32 v156, s54, v141
	v_add_u32_e32 v172, s56, v141
	ds_read_b128 v[144:147], v156
	ds_read_b128 v[148:151], v156 offset:1024
	ds_read_b128 v[152:155], v156 offset:2048
	ds_read_b128 v[156:159], v156 offset:3072
	ds_read_b128 v[160:163], v172
	ds_read_b128 v[164:167], v172 offset:1024
	ds_read_b128 v[168:171], v172 offset:2048
	ds_read_b128 v[172:175], v172 offset:3072
	s_mov_b32 m0, s42
	ds_read_b128 v[176:179], v143
	ds_read_b128 v[180:183], v143 offset:1024
	ds_read_b128 v[184:187], v143 offset:2048
	ds_read_b128 v[188:191], v143 offset:3072
	ds_read_b128 v[192:195], v143 offset:4096
	ds_read_b128 v[200:203], v143 offset:5120
	ds_read_b128 v[204:207], v143 offset:6144
	ds_read_b128 v[208:211], v143 offset:7168
	global_load_lds_dwordx4 v134, s[98:99]
	s_mov_b32 m0, s43
	s_nop 0
	global_load_lds_dwordx4 v132, s[98:99]
	s_add_i32 m0, s14, 0xc000
	s_nop 0
	global_load_lds_dwordx4 v136, s[30:31]
	s_add_i32 m0, s14, 0xe000
	s_nop 0
	global_load_lds_dwordx4 v138, s[30:31]
	s_waitcnt vmcnt(8)
	s_waitcnt lgkmcnt(0)
	s_barrier
	v_mfma_f32_16x16x32_bf16 v[126:129], v[144:147], v[176:179], v[126:129]
	v_mfma_f32_16x16x32_bf16 v[126:129], v[148:151], v[180:183], v[126:129]
	v_mfma_f32_16x16x32_bf16 v[118:121], v[144:147], v[184:187], v[118:121]
	v_mfma_f32_16x16x32_bf16 v[118:121], v[148:151], v[188:191], v[118:121]
	v_mfma_f32_16x16x32_bf16 v[102:105], v[144:147], v[192:195], v[102:105]
	v_mfma_f32_16x16x32_bf16 v[102:105], v[148:151], v[200:203], v[102:105]
	v_mfma_f32_16x16x32_bf16 v[86:89], v[144:147], v[204:207], v[86:89]
	v_mfma_f32_16x16x32_bf16 v[86:89], v[148:151], v[208:211], v[86:89]
	v_mfma_f32_16x16x32_bf16 v[122:125], v[152:155], v[176:179], v[122:125]
	v_mfma_f32_16x16x32_bf16 v[122:125], v[156:159], v[180:183], v[122:125]
	v_mfma_f32_16x16x32_bf16 v[114:117], v[152:155], v[184:187], v[114:117]
	v_mfma_f32_16x16x32_bf16 v[114:117], v[156:159], v[188:191], v[114:117]
	v_mfma_f32_16x16x32_bf16 v[98:101], v[152:155], v[192:195], v[98:101]
	v_mfma_f32_16x16x32_bf16 v[98:101], v[156:159], v[200:203], v[98:101]
	v_mfma_f32_16x16x32_bf16 v[82:85], v[152:155], v[204:207], v[82:85]
	v_mfma_f32_16x16x32_bf16 v[82:85], v[156:159], v[208:211], v[82:85]
	v_mfma_f32_16x16x32_bf16 v[110:113], v[160:163], v[176:179], v[110:113]
	v_mfma_f32_16x16x32_bf16 v[110:113], v[164:167], v[180:183], v[110:113]
	v_mfma_f32_16x16x32_bf16 v[94:97], v[160:163], v[184:187], v[94:97]
	v_mfma_f32_16x16x32_bf16 v[94:97], v[164:167], v[188:191], v[94:97]
	v_mfma_f32_16x16x32_bf16 v[78:81], v[160:163], v[192:195], v[78:81]
	v_mfma_f32_16x16x32_bf16 v[78:81], v[164:167], v[200:203], v[78:81]
	v_mfma_f32_16x16x32_bf16 v[70:73], v[160:163], v[204:207], v[70:73]
	v_mfma_f32_16x16x32_bf16 v[70:73], v[164:167], v[208:211], v[70:73]
	v_mfma_f32_16x16x32_bf16 v[106:109], v[168:171], v[176:179], v[106:109]
	v_mfma_f32_16x16x32_bf16 v[106:109], v[172:175], v[180:183], v[106:109]
	v_mfma_f32_16x16x32_bf16 v[90:93], v[168:171], v[184:187], v[90:93]
	v_mfma_f32_16x16x32_bf16 v[90:93], v[172:175], v[188:191], v[90:93]
	v_mfma_f32_16x16x32_bf16 v[74:77], v[168:171], v[192:195], v[74:77]
	v_mfma_f32_16x16x32_bf16 v[74:77], v[172:175], v[200:203], v[74:77]
	v_mfma_f32_16x16x32_bf16 v[66:69], v[168:171], v[204:207], v[66:69]
	v_mfma_f32_16x16x32_bf16 v[66:69], v[172:175], v[208:211], v[66:69]
	s_barrier
	s_add_i32 s54, s54, s9
	s_mov_b32 m0, s54
	ds_read_b128 v[176:179], v143 offset:16384
	ds_read_b128 v[180:183], v143 offset:17408
	ds_read_b128 v[184:187], v143 offset:18432
	ds_read_b128 v[188:191], v143 offset:19456
	ds_read_b128 v[192:195], v143 offset:20480
	ds_read_b128 v[200:203], v143 offset:21504
	ds_read_b128 v[204:207], v143 offset:22528
	ds_read_b128 v[208:211], v143 offset:23552
	global_load_lds_dwordx4 v0, s[34:35]
	s_add_i32 m0, s54, 0x2000
	s_add_u32 s54, s34, 0x100000
	s_addc_u32 s55, s35, 0
	s_add_i32 s56, s56, s9
	global_load_lds_dwordx4 v130, s[34:35]
	s_mov_b32 m0, s56
	s_nop 0
	global_load_lds_dwordx4 v0, s[54:55]
	s_add_i32 m0, s56, 0x2000
	s_nop 0
	global_load_lds_dwordx4 v130, s[54:55]
	s_waitcnt vmcnt(6)
	s_waitcnt lgkmcnt(0)
	s_barrier
	v_mfma_f32_16x16x32_bf16 v[62:65], v[144:147], v[176:179], v[62:65]
	v_mfma_f32_16x16x32_bf16 v[62:65], v[148:151], v[180:183], v[62:65]
	v_mfma_f32_16x16x32_bf16 v[54:57], v[144:147], v[184:187], v[54:57]
	v_mfma_f32_16x16x32_bf16 v[54:57], v[148:151], v[188:191], v[54:57]
	v_mfma_f32_16x16x32_bf16 v[38:41], v[144:147], v[192:195], v[38:41]
	v_mfma_f32_16x16x32_bf16 v[38:41], v[148:151], v[200:203], v[38:41]
	v_mfma_f32_16x16x32_bf16 v[22:25], v[144:147], v[204:207], v[22:25]
	v_mfma_f32_16x16x32_bf16 v[22:25], v[148:151], v[208:211], v[22:25]
	v_mfma_f32_16x16x32_bf16 v[58:61], v[152:155], v[176:179], v[58:61]
	v_mfma_f32_16x16x32_bf16 v[58:61], v[156:159], v[180:183], v[58:61]
	v_mfma_f32_16x16x32_bf16 v[50:53], v[152:155], v[184:187], v[50:53]
	v_mfma_f32_16x16x32_bf16 v[50:53], v[156:159], v[188:191], v[50:53]
	v_mfma_f32_16x16x32_bf16 v[34:37], v[152:155], v[192:195], v[34:37]
	v_mfma_f32_16x16x32_bf16 v[34:37], v[156:159], v[200:203], v[34:37]
	v_mfma_f32_16x16x32_bf16 v[18:21], v[152:155], v[204:207], v[18:21]
	v_mfma_f32_16x16x32_bf16 v[18:21], v[156:159], v[208:211], v[18:21]
	v_mfma_f32_16x16x32_bf16 v[46:49], v[160:163], v[176:179], v[46:49]
	v_mfma_f32_16x16x32_bf16 v[46:49], v[164:167], v[180:183], v[46:49]
	v_mfma_f32_16x16x32_bf16 v[30:33], v[160:163], v[184:187], v[30:33]
	v_mfma_f32_16x16x32_bf16 v[30:33], v[164:167], v[188:191], v[30:33]
	v_mfma_f32_16x16x32_bf16 v[14:17], v[160:163], v[192:195], v[14:17]
	v_mfma_f32_16x16x32_bf16 v[14:17], v[164:167], v[200:203], v[14:17]
	v_mfma_f32_16x16x32_bf16 v[6:9], v[160:163], v[204:207], v[6:9]
	v_mfma_f32_16x16x32_bf16 v[6:9], v[164:167], v[208:211], v[6:9]
	v_mfma_f32_16x16x32_bf16 v[42:45], v[168:171], v[176:179], v[42:45]
	v_mfma_f32_16x16x32_bf16 v[42:45], v[172:175], v[180:183], v[42:45]
	v_mfma_f32_16x16x32_bf16 v[26:29], v[168:171], v[184:187], v[26:29]
	v_mfma_f32_16x16x32_bf16 v[26:29], v[172:175], v[188:191], v[26:29]
	v_mfma_f32_16x16x32_bf16 v[10:13], v[168:171], v[192:195], v[10:13]
	v_mfma_f32_16x16x32_bf16 v[10:13], v[172:175], v[200:203], v[10:13]
	v_mfma_f32_16x16x32_bf16 v[2:5], v[168:171], v[204:207], v[2:5]
	v_mfma_f32_16x16x32_bf16 v[2:5], v[172:175], v[208:211], v[2:5]
	s_barrier
	s_add_i32 s54, 0, 0x18000
	s_add_i32 s55, 0, 0x1c000
	v_add_u32_e32 v156, s54, v141
	v_add_u32_e32 v172, s55, v141
	ds_read_b128 v[144:147], v156
	ds_read_b128 v[148:151], v156 offset:1024
	ds_read_b128 v[152:155], v156 offset:2048
	ds_read_b128 v[156:159], v156 offset:3072
	ds_read_b128 v[160:163], v172
	ds_read_b128 v[164:167], v172 offset:1024
	ds_read_b128 v[168:171], v172 offset:2048
	ds_read_b128 v[172:175], v172 offset:3072
	s_mov_b32 m0, s14
	ds_read_b128 v[176:179], v143 offset:32768
	ds_read_b128 v[180:183], v143 offset:33792
	ds_read_b128 v[184:187], v143 offset:34816
	ds_read_b128 v[188:191], v143 offset:35840
	ds_read_b128 v[192:195], v143 offset:36864
	ds_read_b128 v[200:203], v143 offset:37888
	ds_read_b128 v[204:207], v143 offset:38912
	ds_read_b128 v[208:211], v143 offset:39936
	global_load_lds_dwordx4 v134, s[40:41]
	s_mov_b32 m0, s15
	s_nop 0
	global_load_lds_dwordx4 v132, s[40:41]
	s_add_u32 s40, s40, 0x100000
	s_addc_u32 s41, s41, 0
	s_mov_b32 m0, s18
	s_nop 0
	global_load_lds_dwordx4 v134, s[40:41]
	s_mov_b32 m0, s19
	s_nop 0
	global_load_lds_dwordx4 v132, s[40:41]
	s_waitcnt vmcnt(8)
	s_waitcnt lgkmcnt(0)
	s_barrier
	v_mfma_f32_16x16x32_bf16 v[126:129], v[144:147], v[176:179], v[126:129]
	v_mfma_f32_16x16x32_bf16 v[126:129], v[148:151], v[180:183], v[126:129]
	v_mfma_f32_16x16x32_bf16 v[118:121], v[144:147], v[184:187], v[118:121]
	v_mfma_f32_16x16x32_bf16 v[118:121], v[148:151], v[188:191], v[118:121]
	v_mfma_f32_16x16x32_bf16 v[102:105], v[144:147], v[192:195], v[102:105]
	v_mfma_f32_16x16x32_bf16 v[102:105], v[148:151], v[200:203], v[102:105]
	v_mfma_f32_16x16x32_bf16 v[86:89], v[144:147], v[204:207], v[86:89]
	v_mfma_f32_16x16x32_bf16 v[86:89], v[148:151], v[208:211], v[86:89]
	v_mfma_f32_16x16x32_bf16 v[122:125], v[152:155], v[176:179], v[122:125]
	v_mfma_f32_16x16x32_bf16 v[122:125], v[156:159], v[180:183], v[122:125]
	v_mfma_f32_16x16x32_bf16 v[114:117], v[152:155], v[184:187], v[114:117]
	v_mfma_f32_16x16x32_bf16 v[114:117], v[156:159], v[188:191], v[114:117]
	v_mfma_f32_16x16x32_bf16 v[98:101], v[152:155], v[192:195], v[98:101]
	v_mfma_f32_16x16x32_bf16 v[98:101], v[156:159], v[200:203], v[98:101]
	v_mfma_f32_16x16x32_bf16 v[82:85], v[152:155], v[204:207], v[82:85]
	v_mfma_f32_16x16x32_bf16 v[82:85], v[156:159], v[208:211], v[82:85]
	v_mfma_f32_16x16x32_bf16 v[110:113], v[160:163], v[176:179], v[110:113]
	v_mfma_f32_16x16x32_bf16 v[110:113], v[164:167], v[180:183], v[110:113]
	v_mfma_f32_16x16x32_bf16 v[94:97], v[160:163], v[184:187], v[94:97]
	v_mfma_f32_16x16x32_bf16 v[94:97], v[164:167], v[188:191], v[94:97]
	v_mfma_f32_16x16x32_bf16 v[78:81], v[160:163], v[192:195], v[78:81]
	v_mfma_f32_16x16x32_bf16 v[78:81], v[164:167], v[200:203], v[78:81]
	v_mfma_f32_16x16x32_bf16 v[70:73], v[160:163], v[204:207], v[70:73]
	v_mfma_f32_16x16x32_bf16 v[70:73], v[164:167], v[208:211], v[70:73]
	v_mfma_f32_16x16x32_bf16 v[106:109], v[168:171], v[176:179], v[106:109]
	v_mfma_f32_16x16x32_bf16 v[106:109], v[172:175], v[180:183], v[106:109]
	v_mfma_f32_16x16x32_bf16 v[90:93], v[168:171], v[184:187], v[90:93]
	v_mfma_f32_16x16x32_bf16 v[90:93], v[172:175], v[188:191], v[90:93]
	v_mfma_f32_16x16x32_bf16 v[74:77], v[168:171], v[192:195], v[74:77]
	v_mfma_f32_16x16x32_bf16 v[74:77], v[172:175], v[200:203], v[74:77]
	v_mfma_f32_16x16x32_bf16 v[66:69], v[168:171], v[204:207], v[66:69]
	v_mfma_f32_16x16x32_bf16 v[66:69], v[172:175], v[208:211], v[66:69]
	s_barrier
	s_add_u32 s98, s34, 0x80
	s_addc_u32 s99, s35, 0
	s_add_i32 s40, s54, s9
	s_mov_b32 m0, s40
	ds_read_b128 v[176:179], v143 offset:49152
	ds_read_b128 v[180:183], v143 offset:50176
	ds_read_b128 v[184:187], v143 offset:51200
	ds_read_b128 v[188:191], v143 offset:52224
	ds_read_b128 v[192:195], v143 offset:53248
	ds_read_b128 v[200:203], v143 offset:54272
	ds_read_b128 v[204:207], v143 offset:55296
	ds_read_b128 v[208:211], v143 offset:56320
	global_load_lds_dwordx4 v0, s[98:99]
	s_add_i32 m0, s40, 0x2000
	s_add_u32 s34, s34, 0x100080
	s_addc_u32 s35, s35, 0
	s_add_i32 s40, s55, s9
	global_load_lds_dwordx4 v130, s[98:99]
	s_mov_b32 m0, s40
	s_nop 0
	global_load_lds_dwordx4 v0, s[34:35]
	s_add_i32 m0, s40, 0x2000
	s_nop 0
	global_load_lds_dwordx4 v130, s[34:35]
	s_waitcnt vmcnt(6)
	s_waitcnt lgkmcnt(0)
	s_barrier
	v_mfma_f32_16x16x32_bf16 v[62:65], v[144:147], v[176:179], v[62:65]
	v_mfma_f32_16x16x32_bf16 v[62:65], v[148:151], v[180:183], v[62:65]
	v_mfma_f32_16x16x32_bf16 v[54:57], v[144:147], v[184:187], v[54:57]
	v_mfma_f32_16x16x32_bf16 v[54:57], v[148:151], v[188:191], v[54:57]
	v_mfma_f32_16x16x32_bf16 v[38:41], v[144:147], v[192:195], v[38:41]
	v_mfma_f32_16x16x32_bf16 v[38:41], v[148:151], v[200:203], v[38:41]
	v_mfma_f32_16x16x32_bf16 v[22:25], v[144:147], v[204:207], v[22:25]
	v_mfma_f32_16x16x32_bf16 v[22:25], v[148:151], v[208:211], v[22:25]
	v_mfma_f32_16x16x32_bf16 v[58:61], v[152:155], v[176:179], v[58:61]
	v_mfma_f32_16x16x32_bf16 v[58:61], v[156:159], v[180:183], v[58:61]
	v_mfma_f32_16x16x32_bf16 v[50:53], v[152:155], v[184:187], v[50:53]
	v_mfma_f32_16x16x32_bf16 v[50:53], v[156:159], v[188:191], v[50:53]
	v_mfma_f32_16x16x32_bf16 v[34:37], v[152:155], v[192:195], v[34:37]
	v_mfma_f32_16x16x32_bf16 v[34:37], v[156:159], v[200:203], v[34:37]
	v_mfma_f32_16x16x32_bf16 v[18:21], v[152:155], v[204:207], v[18:21]
	v_mfma_f32_16x16x32_bf16 v[18:21], v[156:159], v[208:211], v[18:21]
	v_mfma_f32_16x16x32_bf16 v[46:49], v[160:163], v[176:179], v[46:49]
	v_mfma_f32_16x16x32_bf16 v[46:49], v[164:167], v[180:183], v[46:49]
	v_mfma_f32_16x16x32_bf16 v[30:33], v[160:163], v[184:187], v[30:33]
	v_mfma_f32_16x16x32_bf16 v[30:33], v[164:167], v[188:191], v[30:33]
	v_mfma_f32_16x16x32_bf16 v[14:17], v[160:163], v[192:195], v[14:17]
	v_mfma_f32_16x16x32_bf16 v[14:17], v[164:167], v[200:203], v[14:17]
	v_mfma_f32_16x16x32_bf16 v[6:9], v[160:163], v[204:207], v[6:9]
	v_mfma_f32_16x16x32_bf16 v[6:9], v[164:167], v[208:211], v[6:9]
	v_mfma_f32_16x16x32_bf16 v[42:45], v[168:171], v[176:179], v[42:45]
	v_mfma_f32_16x16x32_bf16 v[42:45], v[172:175], v[180:183], v[42:45]
	v_mfma_f32_16x16x32_bf16 v[26:29], v[168:171], v[184:187], v[26:29]
	v_mfma_f32_16x16x32_bf16 v[26:29], v[172:175], v[188:191], v[26:29]
	v_mfma_f32_16x16x32_bf16 v[10:13], v[168:171], v[192:195], v[10:13]
	v_mfma_f32_16x16x32_bf16 v[10:13], v[172:175], v[200:203], v[10:13]
	v_mfma_f32_16x16x32_bf16 v[2:5], v[168:171], v[204:207], v[2:5]
	v_mfma_f32_16x16x32_bf16 v[2:5], v[172:175], v[208:211], v[2:5]
	s_barrier
	s_add_i32 s53, s53, 2
	s_add_u32 s30, s30, 0x100
	s_addc_u32 s31, s31, 0
	s_add_u32 s51, s51, 0x100
	s_addc_u32 s52, s52, 0
	s_cmp_gt_u32 s53, 61
	s_cbranch_scc0 .LBB0_801
	s_and_b64 vcc, exec, s[20:21]
	s_cbranch_vccz .LBB0_804
	s_barrier
